# grid-barrier leader: XGEN release of the local workgroups issued before the leader's own buffer_inv sc1 (10 barrier instances)
# baseline (speedup 1.0000x reference)
.LBB0_89:
	s_or_b64 exec, exec, s[6:7]
	s_mov_b64 s[6:7], exec
	v_mbcnt_lo_u32_b32 v2, s6, 0
	v_mbcnt_hi_u32_b32 v2, s7, v2
	v_cmp_eq_u32_e32 vcc, 0, v2
	s_waitcnt vmcnt(0)

	s_and_saveexec_b64 s[20:21], vcc
	s_cbranch_execz .LBB0_91
	s_bcnt1_i32_b64 s6, s[6:7]
	v_mov_b32_e32 v2, 0x2000
	v_mov_b32_e32 v3, s6
	global_atomic_add v2, v3, s[4:5] offset:1024
.LBB0_91:
	s_or_b64 exec, exec, s[20:21]
	buffer_inv sc1
	s_waitcnt vmcnt(0)

.LBB0_171:
	s_or_b64 exec, exec, s[4:5]
	s_mov_b64 s[4:5], exec
	v_mbcnt_lo_u32_b32 v2, s4, 0
	v_mbcnt_hi_u32_b32 v2, s5, v2
	v_cmp_eq_u32_e32 vcc, 0, v2
	s_waitcnt vmcnt(0)

	s_and_saveexec_b64 s[6:7], vcc
	s_cbranch_execz .LBB0_173
	s_bcnt1_i32_b64 s4, s[4:5]
	v_mov_b32_e32 v2, 0x2000
	v_mov_b32_e32 v3, s4
	global_atomic_add v2, v3, s[2:3] offset:1024
.LBB0_173:
	s_or_b64 exec, exec, s[6:7]
	buffer_inv sc1
	s_waitcnt vmcnt(0)

.LBB0_270:
	s_or_b64 exec, exec, s[12:13]
	buffer_inv sc1
	s_waitcnt vmcnt(0)

.LBB0_379:
	s_or_b64 exec, exec, s[10:11]
	s_mov_b64 s[10:11], exec
	v_mbcnt_lo_u32_b32 v2, s10, 0
	v_mbcnt_hi_u32_b32 v2, s11, v2
	v_cmp_eq_u32_e32 vcc, 0, v2
	s_waitcnt vmcnt(0)

	s_and_saveexec_b64 s[12:13], vcc
	s_cbranch_execz .LBB0_381
	s_bcnt1_i32_b64 s10, s[10:11]
	v_mov_b32_e32 v2, s10
	v_readlane_b32 s10, v241, 9
	v_readlane_b32 s11, v241, 10
	s_nop 4
	global_atomic_add v155, v2, s[10:11]

.LBB0_546:
	s_or_b64 exec, exec, s[10:11]
	s_mov_b64 s[10:11], exec
	v_mbcnt_lo_u32_b32 v2, s10, 0
	v_mbcnt_hi_u32_b32 v2, s11, v2
	v_cmp_eq_u32_e32 vcc, 0, v2
	s_waitcnt vmcnt(0)

	s_and_saveexec_b64 s[12:13], vcc
	s_cbranch_execz .LBB0_270
	s_bcnt1_i32_b64 s10, s[10:11]
	v_mov_b32_e32 v2, s10
	v_readlane_b32 s10, v241, 9
	v_readlane_b32 s11, v241, 10
	s_nop 4
	global_atomic_add v155, v2, s[10:11]
	s_branch .LBB0_270

.LBB0_565:
	s_or_b64 exec, exec, s[10:11]
	buffer_inv sc1
	s_waitcnt vmcnt(0)

.LBB0_700:
	s_or_b64 exec, exec, s[8:9]
	s_mov_b64 s[8:9], exec
	v_mbcnt_lo_u32_b32 v2, s8, 0
	v_mbcnt_hi_u32_b32 v2, s9, v2
	v_cmp_eq_u32_e32 vcc, 0, v2
	s_waitcnt vmcnt(0)

	s_and_saveexec_b64 s[10:11], vcc
	s_cbranch_execz .LBB0_702
	s_bcnt1_i32_b64 s8, s[8:9]
	v_mov_b32_e32 v2, s8
	v_readlane_b32 s8, v241, 9
	v_readlane_b32 s9, v241, 10
	s_nop 4
	global_atomic_add v3, v2, s[8:9]

.LBB0_939:
	s_or_b64 exec, exec, s[8:9]
	s_mov_b64 s[8:9], exec
	v_mbcnt_lo_u32_b32 v2, s8, 0
	v_mbcnt_hi_u32_b32 v2, s9, v2
	v_cmp_eq_u32_e32 vcc, 0, v2
	s_waitcnt vmcnt(0)

	s_and_saveexec_b64 s[10:11], vcc
	s_cbranch_execz .LBB0_565
	s_bcnt1_i32_b64 s8, s[8:9]
	v_mov_b32_e32 v2, s8
	v_readlane_b32 s8, v241, 9
	v_readlane_b32 s9, v241, 10
	s_nop 4
	global_atomic_add v3, v2, s[8:9]
	s_branch .LBB0_565
